# GEMM K-loops: priority 1 held through all 32 MFMAs of a matrix segment (the s_setprio 0/1 pair between the two halves dropped)
# baseline (speedup 1.0000x reference)
.LBB0_126:
	ds_read_b128 v[148:151], v159
	ds_read_b128 v[152:155], v159 offset:1024
	ds_read_b128 v[162:165], v159 offset:2048
	ds_read_b128 v[166:169], v159 offset:3072
	ds_read_b128 v[170:173], v160
	ds_read_b128 v[174:177], v160 offset:1024
	ds_read_b128 v[178:181], v160 offset:2048
	ds_read_b128 v[182:185], v160 offset:3072
	s_add_u32 s34, s30, 0xfffc0080
	s_addc_u32 s35, s31, -1
	s_cmp_eq_u32 s72, 12
	s_cselect_b32 s37, s5, s35
	s_cselect_b32 s36, s38, s34
	s_cselect_b32 s35, s39, s71
	s_cselect_b32 s34, s44, s45
	v_lshl_add_u64 v[156:157], s[30:31], 0, v[140:141]
	s_add_i32 m0, s48, 0xc000
	ds_read_b128 v[186:189], v161
	ds_read_b128 v[190:193], v161 offset:1024
	ds_read_b128 v[194:197], v161 offset:2048
	ds_read_b128 v[198:201], v161 offset:3072
	ds_read_b128 v[202:205], v161 offset:4096
	ds_read_b128 v[206:209], v161 offset:5120
	ds_read_b128 v[210:213], v161 offset:6144
	ds_read_b128 v[214:217], v161 offset:7168
	global_load_lds_dwordx4 v[156:157], off
	v_lshl_add_u64 v[156:157], s[30:31], 0, v[142:143]
	s_add_i32 m0, s48, 0xe000
	s_nop 0
	global_load_lds_dwordx4 v[156:157], off
	s_waitcnt vmcnt(8)
	s_waitcnt lgkmcnt(0)
	s_barrier
	s_setprio 1
	s_waitcnt lgkmcnt(0)
	v_mfma_f32_16x16x32_bf16 v[126:129], v[148:151], v[186:189], v[126:129]
	v_mfma_f32_16x16x32_bf16 v[122:125], v[162:165], v[186:189], v[122:125]
	v_mfma_f32_16x16x32_bf16 v[110:113], v[148:151], v[194:197], v[110:113]
	v_mfma_f32_16x16x32_bf16 v[106:109], v[162:165], v[194:197], v[106:109]
	v_mfma_f32_16x16x32_bf16 v[94:97], v[148:151], v[202:205], v[94:97]
	v_mfma_f32_16x16x32_bf16 v[90:93], v[162:165], v[202:205], v[90:93]
	v_mfma_f32_16x16x32_bf16 v[78:81], v[148:151], v[210:213], v[78:81]
	v_mfma_f32_16x16x32_bf16 v[74:77], v[162:165], v[210:213], v[74:77]
	v_mfma_f32_16x16x32_bf16 v[126:129], v[152:155], v[190:193], v[126:129]
	v_mfma_f32_16x16x32_bf16 v[122:125], v[166:169], v[190:193], v[122:125]
	v_mfma_f32_16x16x32_bf16 v[110:113], v[152:155], v[198:201], v[110:113]
	v_mfma_f32_16x16x32_bf16 v[106:109], v[166:169], v[198:201], v[106:109]
	v_mfma_f32_16x16x32_bf16 v[94:97], v[152:155], v[206:209], v[94:97]
	v_mfma_f32_16x16x32_bf16 v[90:93], v[166:169], v[206:209], v[90:93]
	v_mfma_f32_16x16x32_bf16 v[78:81], v[152:155], v[214:217], v[78:81]
	v_mfma_f32_16x16x32_bf16 v[74:77], v[166:169], v[214:217], v[74:77]
	v_mfma_f32_16x16x32_bf16 v[118:121], v[170:173], v[186:189], v[118:121]
	v_mfma_f32_16x16x32_bf16 v[114:117], v[178:181], v[186:189], v[114:117]
	v_mfma_f32_16x16x32_bf16 v[102:105], v[170:173], v[194:197], v[102:105]
	v_mfma_f32_16x16x32_bf16 v[98:101], v[178:181], v[194:197], v[98:101]
	v_mfma_f32_16x16x32_bf16 v[86:89], v[170:173], v[202:205], v[86:89]
	v_mfma_f32_16x16x32_bf16 v[82:85], v[178:181], v[202:205], v[82:85]
	v_mfma_f32_16x16x32_bf16 v[70:73], v[170:173], v[210:213], v[70:73]
	v_mfma_f32_16x16x32_bf16 v[66:69], v[178:181], v[210:213], v[66:69]
	v_mfma_f32_16x16x32_bf16 v[118:121], v[174:177], v[190:193], v[118:121]
	v_mfma_f32_16x16x32_bf16 v[114:117], v[182:185], v[190:193], v[114:117]
	v_mfma_f32_16x16x32_bf16 v[102:105], v[174:177], v[198:201], v[102:105]
	v_mfma_f32_16x16x32_bf16 v[98:101], v[182:185], v[198:201], v[98:101]
	v_mfma_f32_16x16x32_bf16 v[86:89], v[174:177], v[206:209], v[86:89]
	v_mfma_f32_16x16x32_bf16 v[82:85], v[182:185], v[206:209], v[82:85]
	s_setprio 2
	s_barrier
	v_mfma_f32_16x16x32_bf16 v[70:73], v[174:177], v[214:217], v[70:73]
	v_mfma_f32_16x16x32_bf16 v[66:69], v[182:185], v[214:217], v[66:69]
	s_setprio 0
	s_add_i32 s73, s65, s47
	v_lshl_add_u64 v[156:157], s[34:35], 0, v[132:133]
	s_mov_b32 m0, s73
	ds_read_b128 v[186:189], v161 offset:16384
	ds_read_b128 v[190:193], v161 offset:17408
	ds_read_b128 v[194:197], v161 offset:18432
	ds_read_b128 v[198:201], v161 offset:19456
	ds_read_b128 v[202:205], v161 offset:20480
	ds_read_b128 v[206:209], v161 offset:21504
	ds_read_b128 v[210:213], v161 offset:22528
	ds_read_b128 v[214:217], v161 offset:23552
	global_load_lds_dwordx4 v[156:157], off
	s_add_i32 m0, s73, 0x2000
	s_add_u32 s74, s34, 0x40000
	v_lshl_add_u64 v[218:219], s[34:35], 0, v[136:137]
	s_addc_u32 s75, s35, 0
	s_add_i32 s73, s66, s47
	global_load_lds_dwordx4 v[218:219], off
	v_lshl_add_u64 v[220:221], s[74:75], 0, v[132:133]
	s_mov_b32 m0, s73
	v_lshl_add_u64 v[222:223], s[36:37], 0, v[134:135]
	global_load_lds_dwordx4 v[220:221], off
	v_lshl_add_u64 v[220:221], s[74:75], 0, v[136:137]
	s_add_i32 m0, s73, 0x2000
	s_nop 0
	global_load_lds_dwordx4 v[220:221], off
	v_lshl_add_u64 v[220:221], s[36:37], 0, v[130:131]
	s_mov_b32 m0, s48
	s_nop 0
	global_load_lds_dwordx4 v[220:221], off
	s_mov_b32 m0, s49
	s_nop 0
	global_load_lds_dwordx4 v[222:223], off
	s_waitcnt vmcnt(8)
	s_waitcnt lgkmcnt(0)
	s_barrier
	s_setprio 1
	s_waitcnt lgkmcnt(0)
	v_mfma_f32_16x16x32_bf16 v[62:65], v[148:151], v[186:189], v[62:65]
	v_mfma_f32_16x16x32_bf16 v[58:61], v[162:165], v[186:189], v[58:61]
	v_mfma_f32_16x16x32_bf16 v[46:49], v[148:151], v[194:197], v[46:49]
	v_mfma_f32_16x16x32_bf16 v[42:45], v[162:165], v[194:197], v[42:45]
	v_mfma_f32_16x16x32_bf16 v[30:33], v[148:151], v[202:205], v[30:33]
	v_mfma_f32_16x16x32_bf16 v[26:29], v[162:165], v[202:205], v[26:29]
	v_mfma_f32_16x16x32_bf16 v[14:17], v[148:151], v[210:213], v[14:17]
	v_mfma_f32_16x16x32_bf16 v[10:13], v[162:165], v[210:213], v[10:13]
	v_mfma_f32_16x16x32_bf16 v[62:65], v[152:155], v[190:193], v[62:65]
	v_mfma_f32_16x16x32_bf16 v[58:61], v[166:169], v[190:193], v[58:61]
	v_mfma_f32_16x16x32_bf16 v[46:49], v[152:155], v[198:201], v[46:49]
	v_mfma_f32_16x16x32_bf16 v[42:45], v[166:169], v[198:201], v[42:45]
	v_mfma_f32_16x16x32_bf16 v[30:33], v[152:155], v[206:209], v[30:33]
	v_mfma_f32_16x16x32_bf16 v[26:29], v[166:169], v[206:209], v[26:29]
	v_mfma_f32_16x16x32_bf16 v[14:17], v[152:155], v[214:217], v[14:17]
	v_mfma_f32_16x16x32_bf16 v[10:13], v[166:169], v[214:217], v[10:13]
	v_mfma_f32_16x16x32_bf16 v[54:57], v[170:173], v[186:189], v[54:57]
	v_mfma_f32_16x16x32_bf16 v[50:53], v[178:181], v[186:189], v[50:53]
	v_mfma_f32_16x16x32_bf16 v[38:41], v[170:173], v[194:197], v[38:41]
	v_mfma_f32_16x16x32_bf16 v[34:37], v[178:181], v[194:197], v[34:37]
	v_mfma_f32_16x16x32_bf16 v[22:25], v[170:173], v[202:205], v[22:25]
	v_mfma_f32_16x16x32_bf16 v[18:21], v[178:181], v[202:205], v[18:21]
	v_mfma_f32_16x16x32_bf16 v[6:9], v[170:173], v[210:213], v[6:9]
	v_mfma_f32_16x16x32_bf16 v[2:5], v[178:181], v[210:213], v[2:5]
	v_mfma_f32_16x16x32_bf16 v[54:57], v[174:177], v[190:193], v[54:57]
	v_mfma_f32_16x16x32_bf16 v[50:53], v[182:185], v[190:193], v[50:53]
	v_mfma_f32_16x16x32_bf16 v[38:41], v[174:177], v[198:201], v[38:41]
	v_mfma_f32_16x16x32_bf16 v[34:37], v[182:185], v[198:201], v[34:37]
	v_mfma_f32_16x16x32_bf16 v[22:25], v[174:177], v[206:209], v[22:25]
	v_mfma_f32_16x16x32_bf16 v[18:21], v[182:185], v[206:209], v[18:21]
	s_setprio 2
	s_barrier
	v_mfma_f32_16x16x32_bf16 v[6:9], v[174:177], v[214:217], v[6:9]
	v_mfma_f32_16x16x32_bf16 v[2:5], v[182:185], v[214:217], v[2:5]
	s_setprio 0
	s_add_i32 s73, 0, 0x18000
	v_add_u32_e32 v138, s73, v158
	s_add_i32 s74, 0, 0x1c000
	ds_read_b128 v[148:151], v138
	ds_read_b128 v[152:155], v138 offset:1024
	ds_read_b128 v[162:165], v138 offset:2048
	ds_read_b128 v[166:169], v138 offset:3072
	v_add_u32_e32 v138, s74, v158
	ds_read_b128 v[170:173], v138
	ds_read_b128 v[174:177], v138 offset:1024
	ds_read_b128 v[178:181], v138 offset:2048
	ds_read_b128 v[182:185], v138 offset:3072
	s_add_u32 s36, s36, 0x40000
	s_addc_u32 s37, s37, 0
	s_mov_b32 m0, s50
	v_lshl_add_u64 v[224:225], s[36:37], 0, v[130:131]
	ds_read_b128 v[186:189], v161 offset:32768
	ds_read_b128 v[190:193], v161 offset:33792
	ds_read_b128 v[194:197], v161 offset:34816
	ds_read_b128 v[198:201], v161 offset:35840
	ds_read_b128 v[202:205], v161 offset:36864
	ds_read_b128 v[206:209], v161 offset:37888
	ds_read_b128 v[210:213], v161 offset:38912
	ds_read_b128 v[214:217], v161 offset:39936
	global_load_lds_dwordx4 v[224:225], off
	v_lshl_add_u64 v[224:225], s[36:37], 0, v[134:135]
	s_mov_b32 m0, s51
	s_nop 0
	global_load_lds_dwordx4 v[224:225], off
	s_waitcnt vmcnt(8)
	s_waitcnt lgkmcnt(0)
	s_barrier
	s_setprio 1
	s_waitcnt lgkmcnt(0)
	v_mfma_f32_16x16x32_bf16 v[126:129], v[148:151], v[186:189], v[126:129]
	v_mfma_f32_16x16x32_bf16 v[122:125], v[162:165], v[186:189], v[122:125]
	v_mfma_f32_16x16x32_bf16 v[110:113], v[148:151], v[194:197], v[110:113]
	v_mfma_f32_16x16x32_bf16 v[106:109], v[162:165], v[194:197], v[106:109]
	v_mfma_f32_16x16x32_bf16 v[94:97], v[148:151], v[202:205], v[94:97]
	v_mfma_f32_16x16x32_bf16 v[90:93], v[162:165], v[202:205], v[90:93]
	v_mfma_f32_16x16x32_bf16 v[78:81], v[148:151], v[210:213], v[78:81]
	v_mfma_f32_16x16x32_bf16 v[74:77], v[162:165], v[210:213], v[74:77]
	v_mfma_f32_16x16x32_bf16 v[126:129], v[152:155], v[190:193], v[126:129]
	v_mfma_f32_16x16x32_bf16 v[122:125], v[166:169], v[190:193], v[122:125]
	v_mfma_f32_16x16x32_bf16 v[110:113], v[152:155], v[198:201], v[110:113]
	v_mfma_f32_16x16x32_bf16 v[106:109], v[166:169], v[198:201], v[106:109]
	v_mfma_f32_16x16x32_bf16 v[94:97], v[152:155], v[206:209], v[94:97]
	v_mfma_f32_16x16x32_bf16 v[90:93], v[166:169], v[206:209], v[90:93]
	v_mfma_f32_16x16x32_bf16 v[78:81], v[152:155], v[214:217], v[78:81]
	v_mfma_f32_16x16x32_bf16 v[74:77], v[166:169], v[214:217], v[74:77]
	v_mfma_f32_16x16x32_bf16 v[118:121], v[170:173], v[186:189], v[118:121]
	v_mfma_f32_16x16x32_bf16 v[114:117], v[178:181], v[186:189], v[114:117]
	v_mfma_f32_16x16x32_bf16 v[102:105], v[170:173], v[194:197], v[102:105]
	v_mfma_f32_16x16x32_bf16 v[98:101], v[178:181], v[194:197], v[98:101]
	v_mfma_f32_16x16x32_bf16 v[86:89], v[170:173], v[202:205], v[86:89]
	v_mfma_f32_16x16x32_bf16 v[82:85], v[178:181], v[202:205], v[82:85]
	v_mfma_f32_16x16x32_bf16 v[70:73], v[170:173], v[210:213], v[70:73]
	v_mfma_f32_16x16x32_bf16 v[66:69], v[178:181], v[210:213], v[66:69]
	v_mfma_f32_16x16x32_bf16 v[118:121], v[174:177], v[190:193], v[118:121]
	v_mfma_f32_16x16x32_bf16 v[114:117], v[182:185], v[190:193], v[114:117]
	v_mfma_f32_16x16x32_bf16 v[102:105], v[174:177], v[198:201], v[102:105]
	v_mfma_f32_16x16x32_bf16 v[98:101], v[182:185], v[198:201], v[98:101]
	v_mfma_f32_16x16x32_bf16 v[86:89], v[174:177], v[206:209], v[86:89]
	v_mfma_f32_16x16x32_bf16 v[82:85], v[182:185], v[206:209], v[82:85]
	s_setprio 2
	s_barrier
	v_mfma_f32_16x16x32_bf16 v[70:73], v[174:177], v[214:217], v[70:73]
	v_mfma_f32_16x16x32_bf16 v[66:69], v[182:185], v[214:217], v[66:69]
	s_setprio 0
	s_add_i32 s36, s73, s47
	v_lshl_add_u64 v[156:157], v[156:157], 0, s[14:15]
	s_mov_b32 m0, s36
	ds_read_b128 v[186:189], v161 offset:49152
	ds_read_b128 v[190:193], v161 offset:50176
	ds_read_b128 v[194:197], v161 offset:51200
	ds_read_b128 v[198:201], v161 offset:52224
	ds_read_b128 v[202:205], v161 offset:53248
	ds_read_b128 v[206:209], v161 offset:54272
	ds_read_b128 v[210:213], v161 offset:55296
	ds_read_b128 v[214:217], v161 offset:56320
	global_load_lds_dwordx4 v[156:157], off
	s_add_i32 m0, s36, 0x2000
	s_add_u32 s34, s34, 0x40080
	v_lshl_add_u64 v[156:157], v[218:219], 0, s[14:15]
	s_addc_u32 s35, s35, 0
	s_add_i32 s36, s74, s47
	global_load_lds_dwordx4 v[156:157], off
	v_lshl_add_u64 v[156:157], s[34:35], 0, v[132:133]
	s_mov_b32 m0, s36
	s_nop 0
	global_load_lds_dwordx4 v[156:157], off
	v_lshl_add_u64 v[156:157], s[34:35], 0, v[136:137]
	s_add_i32 m0, s36, 0x2000
	s_nop 0
	global_load_lds_dwordx4 v[156:157], off
	v_lshl_add_u64 v[156:157], v[220:221], 0, s[14:15]
	s_mov_b32 m0, s62
	s_nop 0
	global_load_lds_dwordx4 v[156:157], off
	v_lshl_add_u64 v[156:157], v[222:223], 0, s[14:15]
	s_mov_b32 m0, s63
	s_nop 0
	global_load_lds_dwordx4 v[156:157], off
	s_waitcnt vmcnt(8)
	s_waitcnt lgkmcnt(0)
	s_barrier
	s_setprio 1
	s_waitcnt lgkmcnt(0)
	v_mfma_f32_16x16x32_bf16 v[62:65], v[148:151], v[186:189], v[62:65]
	v_mfma_f32_16x16x32_bf16 v[58:61], v[162:165], v[186:189], v[58:61]
	v_mfma_f32_16x16x32_bf16 v[46:49], v[148:151], v[194:197], v[46:49]
	v_mfma_f32_16x16x32_bf16 v[42:45], v[162:165], v[194:197], v[42:45]
	v_mfma_f32_16x16x32_bf16 v[30:33], v[148:151], v[202:205], v[30:33]
	v_mfma_f32_16x16x32_bf16 v[26:29], v[162:165], v[202:205], v[26:29]
	v_mfma_f32_16x16x32_bf16 v[14:17], v[148:151], v[210:213], v[14:17]
	v_mfma_f32_16x16x32_bf16 v[10:13], v[162:165], v[210:213], v[10:13]
	v_mfma_f32_16x16x32_bf16 v[62:65], v[152:155], v[190:193], v[62:65]
	v_mfma_f32_16x16x32_bf16 v[58:61], v[166:169], v[190:193], v[58:61]
	v_mfma_f32_16x16x32_bf16 v[46:49], v[152:155], v[198:201], v[46:49]
	v_mfma_f32_16x16x32_bf16 v[42:45], v[166:169], v[198:201], v[42:45]
	v_mfma_f32_16x16x32_bf16 v[30:33], v[152:155], v[206:209], v[30:33]
	v_mfma_f32_16x16x32_bf16 v[26:29], v[166:169], v[206:209], v[26:29]
	v_mfma_f32_16x16x32_bf16 v[14:17], v[152:155], v[214:217], v[14:17]
	v_mfma_f32_16x16x32_bf16 v[10:13], v[166:169], v[214:217], v[10:13]
	v_mfma_f32_16x16x32_bf16 v[54:57], v[170:173], v[186:189], v[54:57]
	v_mfma_f32_16x16x32_bf16 v[50:53], v[178:181], v[186:189], v[50:53]
	v_mfma_f32_16x16x32_bf16 v[38:41], v[170:173], v[194:197], v[38:41]
	v_mfma_f32_16x16x32_bf16 v[34:37], v[178:181], v[194:197], v[34:37]
	v_mfma_f32_16x16x32_bf16 v[22:25], v[170:173], v[202:205], v[22:25]
	v_mfma_f32_16x16x32_bf16 v[18:21], v[178:181], v[202:205], v[18:21]
	v_mfma_f32_16x16x32_bf16 v[6:9], v[170:173], v[210:213], v[6:9]
	v_mfma_f32_16x16x32_bf16 v[2:5], v[178:181], v[210:213], v[2:5]
	v_mfma_f32_16x16x32_bf16 v[54:57], v[174:177], v[190:193], v[54:57]
	v_mfma_f32_16x16x32_bf16 v[50:53], v[182:185], v[190:193], v[50:53]
	v_mfma_f32_16x16x32_bf16 v[38:41], v[174:177], v[198:201], v[38:41]
	v_mfma_f32_16x16x32_bf16 v[34:37], v[182:185], v[198:201], v[34:37]
	v_mfma_f32_16x16x32_bf16 v[22:25], v[174:177], v[206:209], v[22:25]
	v_mfma_f32_16x16x32_bf16 v[18:21], v[182:185], v[206:209], v[18:21]
	s_setprio 2
	s_barrier
	v_mfma_f32_16x16x32_bf16 v[6:9], v[174:177], v[214:217], v[6:9]
	v_mfma_f32_16x16x32_bf16 v[2:5], v[182:185], v[214:217], v[2:5]
	s_setprio 0
	s_add_i32 s72, s72, 2
	s_add_u32 s30, s30, 0x100
	s_addc_u32 s31, s31, 0
	s_add_u32 s45, s45, 0x100
	s_addc_u32 s71, s71, 0
	s_cmp_gt_u32 s72, 13
	s_cbranch_scc0 .LBB0_126
	s_and_b64 vcc, exec, s[18:19]
	s_cbranch_vccz .LBB0_129
	s_barrier

.LBB0_761:
	v_add_u32_e32 v164, s62, v150
	v_add_u32_e32 v180, s63, v150
	s_add_u32 s34, s16, s26
	ds_read_b128 v[152:155], v164
	ds_read_b128 v[156:159], v164 offset:1024
	ds_read_b128 v[160:163], v164 offset:2048
	ds_read_b128 v[164:167], v164 offset:3072
	ds_read_b128 v[168:171], v180
	ds_read_b128 v[172:175], v180 offset:1024
	ds_read_b128 v[176:179], v180 offset:2048
	ds_read_b128 v[180:183], v180 offset:3072
	s_addc_u32 s35, s17, s27
	s_add_u32 s34, s34, 0x100
	s_addc_u32 s35, s35, 0
	s_add_u32 s68, s21, s26
	s_addc_u32 s69, s66, s27
	s_cmpk_eq_i32 s26, 0xf00
	s_cselect_b32 s37, s29, s35
	s_cselect_b32 s36, s28, s34
	s_cselect_b32 s35, s31, s69
	s_cselect_b32 s34, s30, s68
	v_lshl_add_u64 v[216:217], v[146:147], 0, s[26:27]
	s_add_i32 m0, s15, 0xc000
	ds_read_b128 v[184:187], v151
	ds_read_b128 v[188:191], v151 offset:1024
	ds_read_b128 v[192:195], v151 offset:2048
	ds_read_b128 v[196:199], v151 offset:3072
	ds_read_b128 v[200:203], v151 offset:4096
	ds_read_b128 v[204:207], v151 offset:5120
	ds_read_b128 v[208:211], v151 offset:6144
	ds_read_b128 v[212:215], v151 offset:7168
	global_load_lds_dwordx4 v[216:217], off
	v_lshl_add_u64 v[216:217], v[148:149], 0, s[26:27]
	s_add_i32 m0, s15, 0xe000
	s_nop 0
	global_load_lds_dwordx4 v[216:217], off
	s_waitcnt vmcnt(8)
	s_waitcnt lgkmcnt(0)
	s_barrier
	s_setprio 1
	s_waitcnt lgkmcnt(0)
	v_mfma_f32_16x16x32_bf16 v[126:129], v[152:155], v[184:187], v[126:129]
	v_mfma_f32_16x16x32_bf16 v[122:125], v[160:163], v[184:187], v[122:125]
	v_mfma_f32_16x16x32_bf16 v[118:121], v[152:155], v[192:195], v[118:121]
	v_mfma_f32_16x16x32_bf16 v[114:117], v[160:163], v[192:195], v[114:117]
	v_mfma_f32_16x16x32_bf16 v[94:97], v[152:155], v[200:203], v[94:97]
	v_mfma_f32_16x16x32_bf16 v[90:93], v[160:163], v[200:203], v[90:93]
	v_mfma_f32_16x16x32_bf16 v[86:89], v[152:155], v[208:211], v[86:89]
	v_mfma_f32_16x16x32_bf16 v[82:85], v[160:163], v[208:211], v[82:85]
	v_mfma_f32_16x16x32_bf16 v[126:129], v[156:159], v[188:191], v[126:129]
	v_mfma_f32_16x16x32_bf16 v[122:125], v[164:167], v[188:191], v[122:125]
	v_mfma_f32_16x16x32_bf16 v[118:121], v[156:159], v[196:199], v[118:121]
	v_mfma_f32_16x16x32_bf16 v[114:117], v[164:167], v[196:199], v[114:117]
	v_mfma_f32_16x16x32_bf16 v[94:97], v[156:159], v[204:207], v[94:97]
	v_mfma_f32_16x16x32_bf16 v[90:93], v[164:167], v[204:207], v[90:93]
	v_mfma_f32_16x16x32_bf16 v[86:89], v[156:159], v[212:215], v[86:89]
	v_mfma_f32_16x16x32_bf16 v[82:85], v[164:167], v[212:215], v[82:85]
	v_mfma_f32_16x16x32_bf16 v[110:113], v[168:171], v[184:187], v[110:113]
	v_mfma_f32_16x16x32_bf16 v[106:109], v[176:179], v[184:187], v[106:109]
	v_mfma_f32_16x16x32_bf16 v[102:105], v[168:171], v[192:195], v[102:105]
	v_mfma_f32_16x16x32_bf16 v[98:101], v[176:179], v[192:195], v[98:101]
	v_mfma_f32_16x16x32_bf16 v[78:81], v[168:171], v[200:203], v[78:81]
	v_mfma_f32_16x16x32_bf16 v[74:77], v[176:179], v[200:203], v[74:77]
	v_mfma_f32_16x16x32_bf16 v[70:73], v[168:171], v[208:211], v[70:73]
	v_mfma_f32_16x16x32_bf16 v[66:69], v[176:179], v[208:211], v[66:69]
	v_mfma_f32_16x16x32_bf16 v[110:113], v[172:175], v[188:191], v[110:113]
	v_mfma_f32_16x16x32_bf16 v[106:109], v[180:183], v[188:191], v[106:109]
	v_mfma_f32_16x16x32_bf16 v[102:105], v[172:175], v[196:199], v[102:105]
	v_mfma_f32_16x16x32_bf16 v[98:101], v[180:183], v[196:199], v[98:101]
	v_mfma_f32_16x16x32_bf16 v[78:81], v[172:175], v[204:207], v[78:81]
	v_mfma_f32_16x16x32_bf16 v[74:77], v[180:183], v[204:207], v[74:77]
	s_setprio 2
	s_barrier
	v_mfma_f32_16x16x32_bf16 v[70:73], v[172:175], v[212:215], v[70:73]
	v_mfma_f32_16x16x32_bf16 v[66:69], v[180:183], v[212:215], v[66:69]
	s_setprio 0
	s_add_i32 s68, s62, s48
	v_lshl_add_u64 v[216:217], s[34:35], 0, v[132:133]
	s_mov_b32 m0, s68
	ds_read_b128 v[184:187], v151 offset:16384
	ds_read_b128 v[188:191], v151 offset:17408
	ds_read_b128 v[192:195], v151 offset:18432
	ds_read_b128 v[196:199], v151 offset:19456
	ds_read_b128 v[200:203], v151 offset:20480
	ds_read_b128 v[204:207], v151 offset:21504
	ds_read_b128 v[208:211], v151 offset:22528
	ds_read_b128 v[212:215], v151 offset:23552
	global_load_lds_dwordx4 v[216:217], off
	s_add_i32 m0, s68, 0x2000
	s_add_u32 s68, s34, 0x80000
	v_lshl_add_u64 v[218:219], s[34:35], 0, v[136:137]
	s_addc_u32 s69, s35, 0
	s_add_i32 s70, s63, s48
	global_load_lds_dwordx4 v[218:219], off
	v_lshl_add_u64 v[220:221], s[68:69], 0, v[132:133]
	s_mov_b32 m0, s70
	v_lshl_add_u64 v[222:223], s[36:37], 0, v[134:135]
	global_load_lds_dwordx4 v[220:221], off
	v_lshl_add_u64 v[220:221], s[68:69], 0, v[136:137]
	s_add_i32 m0, s70, 0x2000
	s_nop 0
	global_load_lds_dwordx4 v[220:221], off
	v_lshl_add_u64 v[220:221], s[36:37], 0, v[130:131]
	s_mov_b32 m0, s15
	s_nop 0
	global_load_lds_dwordx4 v[220:221], off
	s_mov_b32 m0, s50
	s_nop 0
	global_load_lds_dwordx4 v[222:223], off
	s_waitcnt vmcnt(8)
	s_waitcnt lgkmcnt(0)
	s_barrier
	s_setprio 1
	s_waitcnt lgkmcnt(0)
	v_mfma_f32_16x16x32_bf16 v[62:65], v[152:155], v[184:187], v[62:65]
	v_mfma_f32_16x16x32_bf16 v[58:61], v[160:163], v[184:187], v[58:61]
	v_mfma_f32_16x16x32_bf16 v[54:57], v[152:155], v[192:195], v[54:57]
	v_mfma_f32_16x16x32_bf16 v[50:53], v[160:163], v[192:195], v[50:53]
	v_mfma_f32_16x16x32_bf16 v[30:33], v[152:155], v[200:203], v[30:33]
	v_mfma_f32_16x16x32_bf16 v[26:29], v[160:163], v[200:203], v[26:29]
	v_mfma_f32_16x16x32_bf16 v[22:25], v[152:155], v[208:211], v[22:25]
	v_mfma_f32_16x16x32_bf16 v[18:21], v[160:163], v[208:211], v[18:21]
	v_mfma_f32_16x16x32_bf16 v[62:65], v[156:159], v[188:191], v[62:65]
	v_mfma_f32_16x16x32_bf16 v[58:61], v[164:167], v[188:191], v[58:61]
	v_mfma_f32_16x16x32_bf16 v[54:57], v[156:159], v[196:199], v[54:57]
	v_mfma_f32_16x16x32_bf16 v[50:53], v[164:167], v[196:199], v[50:53]
	v_mfma_f32_16x16x32_bf16 v[30:33], v[156:159], v[204:207], v[30:33]
	v_mfma_f32_16x16x32_bf16 v[26:29], v[164:167], v[204:207], v[26:29]
	v_mfma_f32_16x16x32_bf16 v[22:25], v[156:159], v[212:215], v[22:25]
	v_mfma_f32_16x16x32_bf16 v[18:21], v[164:167], v[212:215], v[18:21]
	v_mfma_f32_16x16x32_bf16 v[46:49], v[168:171], v[184:187], v[46:49]
	v_mfma_f32_16x16x32_bf16 v[42:45], v[176:179], v[184:187], v[42:45]
	v_mfma_f32_16x16x32_bf16 v[38:41], v[168:171], v[192:195], v[38:41]
	v_mfma_f32_16x16x32_bf16 v[34:37], v[176:179], v[192:195], v[34:37]
	v_mfma_f32_16x16x32_bf16 v[14:17], v[168:171], v[200:203], v[14:17]
	v_mfma_f32_16x16x32_bf16 v[10:13], v[176:179], v[200:203], v[10:13]
	v_mfma_f32_16x16x32_bf16 v[6:9], v[168:171], v[208:211], v[6:9]
	v_mfma_f32_16x16x32_bf16 v[2:5], v[176:179], v[208:211], v[2:5]
	v_mfma_f32_16x16x32_bf16 v[46:49], v[172:175], v[188:191], v[46:49]
	v_mfma_f32_16x16x32_bf16 v[42:45], v[180:183], v[188:191], v[42:45]
	v_mfma_f32_16x16x32_bf16 v[38:41], v[172:175], v[196:199], v[38:41]
	v_mfma_f32_16x16x32_bf16 v[34:37], v[180:183], v[196:199], v[34:37]
	v_mfma_f32_16x16x32_bf16 v[14:17], v[172:175], v[204:207], v[14:17]
	v_mfma_f32_16x16x32_bf16 v[10:13], v[180:183], v[204:207], v[10:13]
	s_setprio 2
	s_barrier
	v_mfma_f32_16x16x32_bf16 v[6:9], v[172:175], v[212:215], v[6:9]
	v_mfma_f32_16x16x32_bf16 v[2:5], v[180:183], v[212:215], v[2:5]
	s_setprio 0
	s_add_i32 s68, 0, 0x18000
	s_add_i32 s69, 0, 0x1c000
	v_add_u32_e32 v164, s68, v150
	v_add_u32_e32 v180, s69, v150
	ds_read_b128 v[152:155], v164
	ds_read_b128 v[156:159], v164 offset:1024
	ds_read_b128 v[160:163], v164 offset:2048
	ds_read_b128 v[164:167], v164 offset:3072
	ds_read_b128 v[168:171], v180
	ds_read_b128 v[172:175], v180 offset:1024
	ds_read_b128 v[176:179], v180 offset:2048
	ds_read_b128 v[180:183], v180 offset:3072
	s_add_u32 s36, s36, 0x80000
	s_addc_u32 s37, s37, 0
	s_mov_b32 m0, s51
	v_lshl_add_u64 v[224:225], s[36:37], 0, v[130:131]
	ds_read_b128 v[184:187], v151 offset:32768
	ds_read_b128 v[188:191], v151 offset:33792
	ds_read_b128 v[192:195], v151 offset:34816
	ds_read_b128 v[196:199], v151 offset:35840
	ds_read_b128 v[200:203], v151 offset:36864
	ds_read_b128 v[204:207], v151 offset:37888
	ds_read_b128 v[208:211], v151 offset:38912
	ds_read_b128 v[212:215], v151 offset:39936
	global_load_lds_dwordx4 v[224:225], off
	v_lshl_add_u64 v[224:225], s[36:37], 0, v[134:135]
	s_mov_b32 m0, s57
	s_nop 0
	global_load_lds_dwordx4 v[224:225], off
	s_waitcnt vmcnt(8)
	s_waitcnt lgkmcnt(0)
	s_barrier
	s_setprio 1
	s_waitcnt lgkmcnt(0)
	v_mfma_f32_16x16x32_bf16 v[126:129], v[152:155], v[184:187], v[126:129]
	v_mfma_f32_16x16x32_bf16 v[122:125], v[160:163], v[184:187], v[122:125]
	v_mfma_f32_16x16x32_bf16 v[118:121], v[152:155], v[192:195], v[118:121]
	v_mfma_f32_16x16x32_bf16 v[114:117], v[160:163], v[192:195], v[114:117]
	v_mfma_f32_16x16x32_bf16 v[94:97], v[152:155], v[200:203], v[94:97]
	v_mfma_f32_16x16x32_bf16 v[90:93], v[160:163], v[200:203], v[90:93]
	v_mfma_f32_16x16x32_bf16 v[86:89], v[152:155], v[208:211], v[86:89]
	v_mfma_f32_16x16x32_bf16 v[82:85], v[160:163], v[208:211], v[82:85]
	v_mfma_f32_16x16x32_bf16 v[126:129], v[156:159], v[188:191], v[126:129]
	v_mfma_f32_16x16x32_bf16 v[122:125], v[164:167], v[188:191], v[122:125]
	v_mfma_f32_16x16x32_bf16 v[118:121], v[156:159], v[196:199], v[118:121]
	v_mfma_f32_16x16x32_bf16 v[114:117], v[164:167], v[196:199], v[114:117]
	v_mfma_f32_16x16x32_bf16 v[94:97], v[156:159], v[204:207], v[94:97]
	v_mfma_f32_16x16x32_bf16 v[90:93], v[164:167], v[204:207], v[90:93]
	v_mfma_f32_16x16x32_bf16 v[86:89], v[156:159], v[212:215], v[86:89]
	v_mfma_f32_16x16x32_bf16 v[82:85], v[164:167], v[212:215], v[82:85]
	v_mfma_f32_16x16x32_bf16 v[110:113], v[168:171], v[184:187], v[110:113]
	v_mfma_f32_16x16x32_bf16 v[106:109], v[176:179], v[184:187], v[106:109]
	v_mfma_f32_16x16x32_bf16 v[102:105], v[168:171], v[192:195], v[102:105]
	v_mfma_f32_16x16x32_bf16 v[98:101], v[176:179], v[192:195], v[98:101]
	v_mfma_f32_16x16x32_bf16 v[78:81], v[168:171], v[200:203], v[78:81]
	v_mfma_f32_16x16x32_bf16 v[74:77], v[176:179], v[200:203], v[74:77]
	v_mfma_f32_16x16x32_bf16 v[70:73], v[168:171], v[208:211], v[70:73]
	v_mfma_f32_16x16x32_bf16 v[66:69], v[176:179], v[208:211], v[66:69]
	v_mfma_f32_16x16x32_bf16 v[110:113], v[172:175], v[188:191], v[110:113]
	v_mfma_f32_16x16x32_bf16 v[106:109], v[180:183], v[188:191], v[106:109]
	v_mfma_f32_16x16x32_bf16 v[102:105], v[172:175], v[196:199], v[102:105]
	v_mfma_f32_16x16x32_bf16 v[98:101], v[180:183], v[196:199], v[98:101]
	v_mfma_f32_16x16x32_bf16 v[78:81], v[172:175], v[204:207], v[78:81]
	v_mfma_f32_16x16x32_bf16 v[74:77], v[180:183], v[204:207], v[74:77]
	s_setprio 2
	s_barrier
	v_mfma_f32_16x16x32_bf16 v[70:73], v[172:175], v[212:215], v[70:73]
	v_mfma_f32_16x16x32_bf16 v[66:69], v[180:183], v[212:215], v[66:69]
	s_setprio 0
	s_add_i32 s36, s68, s48
	v_lshl_add_u64 v[216:217], v[216:217], 0, s[18:19]
	s_mov_b32 m0, s36
	ds_read_b128 v[184:187], v151 offset:49152
	ds_read_b128 v[188:191], v151 offset:50176
	ds_read_b128 v[192:195], v151 offset:51200
	ds_read_b128 v[196:199], v151 offset:52224
	ds_read_b128 v[200:203], v151 offset:53248
	ds_read_b128 v[204:207], v151 offset:54272
	ds_read_b128 v[208:211], v151 offset:55296
	ds_read_b128 v[212:215], v151 offset:56320
	global_load_lds_dwordx4 v[216:217], off
	s_add_i32 m0, s36, 0x2000
	s_add_u32 s34, s34, 0x80080
	v_lshl_add_u64 v[216:217], v[218:219], 0, s[18:19]
	s_addc_u32 s35, s35, 0
	s_add_i32 s36, s69, s48
	global_load_lds_dwordx4 v[216:217], off
	v_lshl_add_u64 v[216:217], s[34:35], 0, v[132:133]
	s_mov_b32 m0, s36
	s_nop 0
	global_load_lds_dwordx4 v[216:217], off
	v_lshl_add_u64 v[216:217], s[34:35], 0, v[136:137]
	s_add_i32 m0, s36, 0x2000
	s_nop 0
	global_load_lds_dwordx4 v[216:217], off
	v_lshl_add_u64 v[216:217], v[220:221], 0, s[18:19]
	s_mov_b32 m0, s60
	s_nop 0
	global_load_lds_dwordx4 v[216:217], off
	v_lshl_add_u64 v[216:217], v[222:223], 0, s[18:19]
	s_mov_b32 m0, s61
	s_nop 0
	global_load_lds_dwordx4 v[216:217], off
	s_waitcnt vmcnt(8)
	s_waitcnt lgkmcnt(0)
	s_barrier
	s_setprio 1
	s_waitcnt lgkmcnt(0)
	v_mfma_f32_16x16x32_bf16 v[62:65], v[152:155], v[184:187], v[62:65]
	v_mfma_f32_16x16x32_bf16 v[58:61], v[160:163], v[184:187], v[58:61]
	v_mfma_f32_16x16x32_bf16 v[54:57], v[152:155], v[192:195], v[54:57]
	v_mfma_f32_16x16x32_bf16 v[50:53], v[160:163], v[192:195], v[50:53]
	v_mfma_f32_16x16x32_bf16 v[30:33], v[152:155], v[200:203], v[30:33]
	v_mfma_f32_16x16x32_bf16 v[26:29], v[160:163], v[200:203], v[26:29]
	v_mfma_f32_16x16x32_bf16 v[22:25], v[152:155], v[208:211], v[22:25]
	v_mfma_f32_16x16x32_bf16 v[18:21], v[160:163], v[208:211], v[18:21]
	v_mfma_f32_16x16x32_bf16 v[62:65], v[156:159], v[188:191], v[62:65]
	v_mfma_f32_16x16x32_bf16 v[58:61], v[164:167], v[188:191], v[58:61]
	v_mfma_f32_16x16x32_bf16 v[54:57], v[156:159], v[196:199], v[54:57]
	v_mfma_f32_16x16x32_bf16 v[50:53], v[164:167], v[196:199], v[50:53]
	v_mfma_f32_16x16x32_bf16 v[30:33], v[156:159], v[204:207], v[30:33]
	v_mfma_f32_16x16x32_bf16 v[26:29], v[164:167], v[204:207], v[26:29]
	v_mfma_f32_16x16x32_bf16 v[22:25], v[156:159], v[212:215], v[22:25]
	v_mfma_f32_16x16x32_bf16 v[18:21], v[164:167], v[212:215], v[18:21]
	v_mfma_f32_16x16x32_bf16 v[46:49], v[168:171], v[184:187], v[46:49]
	v_mfma_f32_16x16x32_bf16 v[42:45], v[176:179], v[184:187], v[42:45]
	v_mfma_f32_16x16x32_bf16 v[38:41], v[168:171], v[192:195], v[38:41]
	v_mfma_f32_16x16x32_bf16 v[34:37], v[176:179], v[192:195], v[34:37]
	v_mfma_f32_16x16x32_bf16 v[14:17], v[168:171], v[200:203], v[14:17]
	v_mfma_f32_16x16x32_bf16 v[10:13], v[176:179], v[200:203], v[10:13]
	v_mfma_f32_16x16x32_bf16 v[6:9], v[168:171], v[208:211], v[6:9]
	v_mfma_f32_16x16x32_bf16 v[2:5], v[176:179], v[208:211], v[2:5]
	v_mfma_f32_16x16x32_bf16 v[46:49], v[172:175], v[188:191], v[46:49]
	v_mfma_f32_16x16x32_bf16 v[42:45], v[180:183], v[188:191], v[42:45]
	v_mfma_f32_16x16x32_bf16 v[38:41], v[172:175], v[196:199], v[38:41]
	v_mfma_f32_16x16x32_bf16 v[34:37], v[180:183], v[196:199], v[34:37]
	v_mfma_f32_16x16x32_bf16 v[14:17], v[172:175], v[204:207], v[14:17]
	v_mfma_f32_16x16x32_bf16 v[10:13], v[180:183], v[204:207], v[10:13]
	s_setprio 2
	s_barrier
	v_mfma_f32_16x16x32_bf16 v[6:9], v[172:175], v[212:215], v[6:9]
	v_mfma_f32_16x16x32_bf16 v[2:5], v[180:183], v[212:215], v[2:5]
	s_setprio 0
	s_add_i32 s67, s67, 2
	s_add_u32 s26, s26, 0x100
	s_addc_u32 s27, s27, 0
	s_cmp_gt_u32 s67, 29
	s_cbranch_scc0 .LBB0_761
	s_add_u32 s26, s21, 0xffffff00
	s_addc_u32 s27, s66, -1
	s_andn2_b64 vcc, exec, s[6:7]
	s_cbranch_vccnz .LBB0_753
	v_mov_b32_e32 v2, 0
	s_mov_b32 s8, s64
	s_mov_b32 s14, s20
	s_mov_b64 s[26:27], s[24:25]
	s_mov_b64 s[16:17], s[22:23]
	s_mov_b32 s59, s65
	v_mov_b32_e32 v3, v2
	v_mov_b32_e32 v4, v2
	v_mov_b32_e32 v5, v2
	v_mov_b32_e32 v6, v2
	v_mov_b32_e32 v7, v2
	v_mov_b32_e32 v8, v2
	v_mov_b32_e32 v9, v2
	v_mov_b32_e32 v10, v2
	v_mov_b32_e32 v11, v2
	v_mov_b32_e32 v12, v2
	v_mov_b32_e32 v13, v2
	v_mov_b32_e32 v14, v2
	v_mov_b32_e32 v15, v2
	v_mov_b32_e32 v16, v2
	v_mov_b32_e32 v17, v2
	v_mov_b32_e32 v34, v2
	v_mov_b32_e32 v35, v2
	v_mov_b32_e32 v36, v2
	v_mov_b32_e32 v37, v2
	v_mov_b32_e32 v38, v2
	v_mov_b32_e32 v39, v2
	v_mov_b32_e32 v40, v2
	v_mov_b32_e32 v41, v2
	v_mov_b32_e32 v42, v2
	v_mov_b32_e32 v43, v2
	v_mov_b32_e32 v44, v2
	v_mov_b32_e32 v45, v2
	v_mov_b32_e32 v46, v2
	v_mov_b32_e32 v47, v2
	v_mov_b32_e32 v48, v2
	v_mov_b32_e32 v49, v2
	v_mov_b32_e32 v18, v2
	v_mov_b32_e32 v19, v2
	v_mov_b32_e32 v20, v2
	v_mov_b32_e32 v21, v2
	v_mov_b32_e32 v22, v2
	v_mov_b32_e32 v23, v2
	v_mov_b32_e32 v24, v2
	v_mov_b32_e32 v25, v2
	v_mov_b32_e32 v26, v2
	v_mov_b32_e32 v27, v2
	v_mov_b32_e32 v28, v2
	v_mov_b32_e32 v29, v2
	v_mov_b32_e32 v30, v2
	v_mov_b32_e32 v31, v2
	v_mov_b32_e32 v32, v2
	v_mov_b32_e32 v33, v2
	v_mov_b32_e32 v50, v2
	v_mov_b32_e32 v51, v2
	v_mov_b32_e32 v52, v2
	v_mov_b32_e32 v53, v2
	v_mov_b32_e32 v54, v2
	v_mov_b32_e32 v55, v2
	v_mov_b32_e32 v56, v2
	v_mov_b32_e32 v57, v2
	v_mov_b32_e32 v58, v2
	v_mov_b32_e32 v59, v2
	v_mov_b32_e32 v60, v2
	v_mov_b32_e32 v61, v2
	v_mov_b32_e32 v62, v2
	v_mov_b32_e32 v63, v2
	v_mov_b32_e32 v64, v2
	v_mov_b32_e32 v65, v2
	v_mov_b32_e32 v66, v2
	v_mov_b32_e32 v67, v2
	v_mov_b32_e32 v68, v2
	v_mov_b32_e32 v69, v2
	v_mov_b32_e32 v70, v2
	v_mov_b32_e32 v71, v2
	v_mov_b32_e32 v72, v2
	v_mov_b32_e32 v73, v2
	v_mov_b32_e32 v74, v2
	v_mov_b32_e32 v75, v2
	v_mov_b32_e32 v76, v2
	v_mov_b32_e32 v77, v2
	v_mov_b32_e32 v78, v2
	v_mov_b32_e32 v79, v2
	v_mov_b32_e32 v80, v2
	v_mov_b32_e32 v81, v2
	v_mov_b32_e32 v98, v2
	v_mov_b32_e32 v99, v2
	v_mov_b32_e32 v100, v2
	v_mov_b32_e32 v101, v2
	v_mov_b32_e32 v102, v2
	v_mov_b32_e32 v103, v2
	v_mov_b32_e32 v104, v2
	v_mov_b32_e32 v105, v2
	v_mov_b32_e32 v106, v2
	v_mov_b32_e32 v107, v2
	v_mov_b32_e32 v108, v2
	v_mov_b32_e32 v109, v2
	v_mov_b32_e32 v110, v2
	v_mov_b32_e32 v111, v2
	v_mov_b32_e32 v112, v2
	v_mov_b32_e32 v113, v2
	v_mov_b32_e32 v82, v2
	v_mov_b32_e32 v83, v2
	v_mov_b32_e32 v84, v2
	v_mov_b32_e32 v85, v2
	v_mov_b32_e32 v86, v2
	v_mov_b32_e32 v87, v2
	v_mov_b32_e32 v88, v2
	v_mov_b32_e32 v89, v2
	v_mov_b32_e32 v90, v2
	v_mov_b32_e32 v91, v2
	v_mov_b32_e32 v92, v2
	v_mov_b32_e32 v93, v2
	v_mov_b32_e32 v94, v2
	v_mov_b32_e32 v95, v2
	v_mov_b32_e32 v96, v2
	v_mov_b32_e32 v97, v2
	v_mov_b32_e32 v114, v2
	v_mov_b32_e32 v115, v2
	v_mov_b32_e32 v116, v2
	v_mov_b32_e32 v117, v2
	v_mov_b32_e32 v118, v2
	v_mov_b32_e32 v119, v2
	v_mov_b32_e32 v120, v2
	v_mov_b32_e32 v121, v2
	v_mov_b32_e32 v122, v2
	v_mov_b32_e32 v123, v2
	v_mov_b32_e32 v124, v2
	v_mov_b32_e32 v125, v2
	v_mov_b32_e32 v126, v2
	v_mov_b32_e32 v127, v2
	v_mov_b32_e32 v128, v2
	v_mov_b32_e32 v129, v2
	s_branch .LBB0_753

.LBB0_965:
	s_cmp_eq_u32 s89, 12
	s_cselect_b64 s[14:15], -1, 0
	s_and_b64 s[14:15], s[14:15], exec
	s_cselect_b32 s15, s54, s88
	s_cselect_b32 s14, s55, s87
	s_add_u32 s90, s12, 0xfffc0080
	s_addc_u32 s91, s13, -1
	s_cmp_eq_u32 s89, 12
	s_cselect_b64 s[42:43], -1, 0
	s_and_b64 s[40:41], s[42:43], exec
	s_cselect_b32 s40, s51, s90
	s_cselect_b32 s41, s50, s91
	s_and_b64 vcc, s[38:39], s[42:43]
	s_and_b64 s[42:43], vcc, exec
	s_cselect_b32 s63, s56, s63
	s_cselect_b32 s64, s86, s64
	s_add_i32 s42, 0, 0x10000
	v_add_u32_e32 v147, s42, v194
	s_add_i32 s43, 0, 0x14000
	ds_read_b128 v[130:133], v147
	ds_read_b128 v[134:137], v147 offset:1024
	ds_read_b128 v[148:151], v147 offset:2048
	ds_read_b128 v[152:155], v147 offset:3072
	v_add_u32_e32 v147, s43, v194
	ds_read_b128 v[156:159], v147
	ds_read_b128 v[160:163], v147 offset:1024
	ds_read_b128 v[164:167], v147 offset:2048
	ds_read_b128 v[168:171], v147 offset:3072
	v_cndmask_b32_e32 v146, v146, v129, vcc
	v_cndmask_b32_e32 v138, v138, v128, vcc
	v_lshl_add_u64 v[228:229], s[12:13], 0, v[144:145]
	s_add_i32 m0, s62, 0xc000
	ds_read_b128 v[196:199], v195
	ds_read_b128 v[200:203], v195 offset:1024
	ds_read_b128 v[204:207], v195 offset:2048
	ds_read_b128 v[208:211], v195 offset:3072
	ds_read_b128 v[212:215], v195 offset:4096
	ds_read_b128 v[216:219], v195 offset:5120
	ds_read_b128 v[220:223], v195 offset:6144
	ds_read_b128 v[224:227], v195 offset:7168
	global_load_lds_dwordx4 v[228:229], off
	v_lshl_add_u64 v[228:229], s[12:13], 0, v[142:143]
	s_add_i32 m0, s62, 0xe000
	s_nop 0
	global_load_lds_dwordx4 v[228:229], off
	s_waitcnt vmcnt(8)
	s_waitcnt lgkmcnt(0)
	s_barrier
	s_setprio 1
	s_waitcnt lgkmcnt(0)
	v_mfma_f32_16x16x32_bf16 v[124:127], v[130:133], v[196:199], v[124:127]
	v_mfma_f32_16x16x32_bf16 v[120:123], v[148:151], v[196:199], v[120:123]
	v_mfma_f32_16x16x32_bf16 v[108:111], v[130:133], v[204:207], v[108:111]
	v_mfma_f32_16x16x32_bf16 v[104:107], v[148:151], v[204:207], v[104:107]
	v_mfma_f32_16x16x32_bf16 v[92:95], v[130:133], v[212:215], v[92:95]
	v_mfma_f32_16x16x32_bf16 v[88:91], v[148:151], v[212:215], v[88:91]
	v_mfma_f32_16x16x32_bf16 v[76:79], v[130:133], v[220:223], v[76:79]
	v_mfma_f32_16x16x32_bf16 v[72:75], v[148:151], v[220:223], v[72:75]
	v_mfma_f32_16x16x32_bf16 v[124:127], v[134:137], v[200:203], v[124:127]
	v_mfma_f32_16x16x32_bf16 v[120:123], v[152:155], v[200:203], v[120:123]
	v_mfma_f32_16x16x32_bf16 v[108:111], v[134:137], v[208:211], v[108:111]
	v_mfma_f32_16x16x32_bf16 v[104:107], v[152:155], v[208:211], v[104:107]
	v_mfma_f32_16x16x32_bf16 v[92:95], v[134:137], v[216:219], v[92:95]
	v_mfma_f32_16x16x32_bf16 v[88:91], v[152:155], v[216:219], v[88:91]
	v_mfma_f32_16x16x32_bf16 v[76:79], v[134:137], v[224:227], v[76:79]
	v_mfma_f32_16x16x32_bf16 v[72:75], v[152:155], v[224:227], v[72:75]
	v_mfma_f32_16x16x32_bf16 v[116:119], v[156:159], v[196:199], v[116:119]
	v_mfma_f32_16x16x32_bf16 v[112:115], v[164:167], v[196:199], v[112:115]
	v_mfma_f32_16x16x32_bf16 v[100:103], v[156:159], v[204:207], v[100:103]
	v_mfma_f32_16x16x32_bf16 v[96:99], v[164:167], v[204:207], v[96:99]
	v_mfma_f32_16x16x32_bf16 v[84:87], v[156:159], v[212:215], v[84:87]
	v_mfma_f32_16x16x32_bf16 v[80:83], v[164:167], v[212:215], v[80:83]
	v_mfma_f32_16x16x32_bf16 v[68:71], v[156:159], v[220:223], v[68:71]
	v_mfma_f32_16x16x32_bf16 v[64:67], v[164:167], v[220:223], v[64:67]
	v_mfma_f32_16x16x32_bf16 v[116:119], v[160:163], v[200:203], v[116:119]
	v_mfma_f32_16x16x32_bf16 v[112:115], v[168:171], v[200:203], v[112:115]
	v_mfma_f32_16x16x32_bf16 v[100:103], v[160:163], v[208:211], v[100:103]
	v_mfma_f32_16x16x32_bf16 v[96:99], v[168:171], v[208:211], v[96:99]
	v_mfma_f32_16x16x32_bf16 v[84:87], v[160:163], v[216:219], v[84:87]
	v_mfma_f32_16x16x32_bf16 v[80:83], v[168:171], v[216:219], v[80:83]
	s_setprio 2
	s_barrier
	v_mfma_f32_16x16x32_bf16 v[68:71], v[160:163], v[224:227], v[68:71]
	v_mfma_f32_16x16x32_bf16 v[64:67], v[168:171], v[224:227], v[64:67]
	s_setprio 0
	s_add_i32 s42, s42, s49
	s_mov_b32 m0, s42
	ds_read_b128 v[196:199], v195 offset:16384
	ds_read_b128 v[200:203], v195 offset:17408
	ds_read_b128 v[204:207], v195 offset:18432
	ds_read_b128 v[208:211], v195 offset:19456
	ds_read_b128 v[212:215], v195 offset:20480
	ds_read_b128 v[216:219], v195 offset:21504
	ds_read_b128 v[220:223], v195 offset:22528
	ds_read_b128 v[224:227], v195 offset:23552
	global_load_lds_dwordx4 v138, s[14:15]
	v_mov_b32_e32 v147, v139
	s_add_i32 m0, s42, 0x2000
	v_lshl_add_u64 v[228:229], s[14:15], 0, v[138:139]
	v_lshl_add_u64 v[230:231], s[14:15], 0, v[146:147]
	global_load_lds_dwordx4 v146, s[14:15]
	s_add_u32 s14, s14, s64
	s_addc_u32 s15, s15, s63
	s_add_i32 s42, s43, s49
	s_mov_b32 m0, s42
	v_lshl_add_u64 v[236:237], s[40:41], 0, v[144:145]
	global_load_lds_dwordx4 v138, s[14:15]
	s_add_i32 m0, s42, 0x2000
	v_lshl_add_u64 v[238:239], s[40:41], 0, v[142:143]
	global_load_lds_dwordx4 v146, s[14:15]
	s_mov_b32 m0, s62
	v_lshl_add_u64 v[232:233], s[14:15], 0, v[138:139]
	global_load_lds_dwordx4 v[236:237], off
	s_mov_b32 m0, s65
	v_lshl_add_u64 v[234:235], s[14:15], 0, v[146:147]
	global_load_lds_dwordx4 v[238:239], off
	s_waitcnt vmcnt(8)
	s_waitcnt lgkmcnt(0)
	s_barrier
	s_setprio 1
	s_waitcnt lgkmcnt(0)
	v_mfma_f32_16x16x32_bf16 v[60:63], v[130:133], v[196:199], v[60:63]
	v_mfma_f32_16x16x32_bf16 v[56:59], v[148:151], v[196:199], v[56:59]
	v_mfma_f32_16x16x32_bf16 v[44:47], v[130:133], v[204:207], v[44:47]
	v_mfma_f32_16x16x32_bf16 v[40:43], v[148:151], v[204:207], v[40:43]
	v_mfma_f32_16x16x32_bf16 v[28:31], v[130:133], v[212:215], v[28:31]
	v_mfma_f32_16x16x32_bf16 v[24:27], v[148:151], v[212:215], v[24:27]
	v_mfma_f32_16x16x32_bf16 v[12:15], v[130:133], v[220:223], v[12:15]
	v_mfma_f32_16x16x32_bf16 v[8:11], v[148:151], v[220:223], v[8:11]
	v_mfma_f32_16x16x32_bf16 v[60:63], v[134:137], v[200:203], v[60:63]
	v_mfma_f32_16x16x32_bf16 v[56:59], v[152:155], v[200:203], v[56:59]
	v_mfma_f32_16x16x32_bf16 v[44:47], v[134:137], v[208:211], v[44:47]
	v_mfma_f32_16x16x32_bf16 v[40:43], v[152:155], v[208:211], v[40:43]
	v_mfma_f32_16x16x32_bf16 v[28:31], v[134:137], v[216:219], v[28:31]
	v_mfma_f32_16x16x32_bf16 v[24:27], v[152:155], v[216:219], v[24:27]
	v_mfma_f32_16x16x32_bf16 v[12:15], v[134:137], v[224:227], v[12:15]
	v_mfma_f32_16x16x32_bf16 v[8:11], v[152:155], v[224:227], v[8:11]
	v_mfma_f32_16x16x32_bf16 v[52:55], v[156:159], v[196:199], v[52:55]
	v_mfma_f32_16x16x32_bf16 v[48:51], v[164:167], v[196:199], v[48:51]
	v_mfma_f32_16x16x32_bf16 v[36:39], v[156:159], v[204:207], v[36:39]
	v_mfma_f32_16x16x32_bf16 v[32:35], v[164:167], v[204:207], v[32:35]
	v_mfma_f32_16x16x32_bf16 v[20:23], v[156:159], v[212:215], v[20:23]
	v_mfma_f32_16x16x32_bf16 v[16:19], v[164:167], v[212:215], v[16:19]
	v_mfma_f32_16x16x32_bf16 v[4:7], v[156:159], v[220:223], v[4:7]
	v_mfma_f32_16x16x32_bf16 v[0:3], v[164:167], v[220:223], v[0:3]
	v_mfma_f32_16x16x32_bf16 v[52:55], v[160:163], v[200:203], v[52:55]
	v_mfma_f32_16x16x32_bf16 v[48:51], v[168:171], v[200:203], v[48:51]
	v_mfma_f32_16x16x32_bf16 v[36:39], v[160:163], v[208:211], v[36:39]
	v_mfma_f32_16x16x32_bf16 v[32:35], v[168:171], v[208:211], v[32:35]
	v_mfma_f32_16x16x32_bf16 v[20:23], v[160:163], v[216:219], v[20:23]
	v_mfma_f32_16x16x32_bf16 v[16:19], v[168:171], v[216:219], v[16:19]
	s_setprio 2
	s_barrier
	v_mfma_f32_16x16x32_bf16 v[4:7], v[160:163], v[224:227], v[4:7]
	v_mfma_f32_16x16x32_bf16 v[0:3], v[168:171], v[224:227], v[0:3]
	s_setprio 0
	s_add_i32 s42, 0, 0x18000
	v_add_u32_e32 v147, s42, v194
	s_add_i32 s43, 0, 0x1c000
	ds_read_b128 v[130:133], v147
	ds_read_b128 v[134:137], v147 offset:1024
	ds_read_b128 v[148:151], v147 offset:2048
	ds_read_b128 v[152:155], v147 offset:3072
	v_add_u32_e32 v147, s43, v194
	ds_read_b128 v[156:159], v147
	ds_read_b128 v[160:163], v147 offset:1024
	ds_read_b128 v[164:167], v147 offset:2048
	ds_read_b128 v[168:171], v147 offset:3072
	s_add_u32 s14, s40, 0x40000
	s_addc_u32 s15, s41, 0
	s_mov_b32 m0, s66
	v_lshl_add_u64 v[240:241], s[14:15], 0, v[144:145]
	ds_read_b128 v[196:199], v195 offset:32768
	ds_read_b128 v[200:203], v195 offset:33792
	ds_read_b128 v[204:207], v195 offset:34816
	ds_read_b128 v[208:211], v195 offset:35840
	ds_read_b128 v[212:215], v195 offset:36864
	ds_read_b128 v[216:219], v195 offset:37888
	ds_read_b128 v[220:223], v195 offset:38912
	ds_read_b128 v[224:227], v195 offset:39936
	global_load_lds_dwordx4 v[240:241], off
	v_lshl_add_u64 v[240:241], s[14:15], 0, v[142:143]
	s_mov_b32 m0, s67
	s_nop 0
	global_load_lds_dwordx4 v[240:241], off
	s_waitcnt vmcnt(8)
	s_waitcnt lgkmcnt(0)
	s_barrier
	s_setprio 1
	s_waitcnt lgkmcnt(0)
	v_mfma_f32_16x16x32_bf16 v[124:127], v[130:133], v[196:199], v[124:127]
	v_mfma_f32_16x16x32_bf16 v[120:123], v[148:151], v[196:199], v[120:123]
	v_mfma_f32_16x16x32_bf16 v[108:111], v[130:133], v[204:207], v[108:111]
	v_mfma_f32_16x16x32_bf16 v[104:107], v[148:151], v[204:207], v[104:107]
	v_mfma_f32_16x16x32_bf16 v[92:95], v[130:133], v[212:215], v[92:95]
	v_mfma_f32_16x16x32_bf16 v[88:91], v[148:151], v[212:215], v[88:91]
	v_mfma_f32_16x16x32_bf16 v[76:79], v[130:133], v[220:223], v[76:79]
	v_mfma_f32_16x16x32_bf16 v[72:75], v[148:151], v[220:223], v[72:75]
	v_mfma_f32_16x16x32_bf16 v[124:127], v[134:137], v[200:203], v[124:127]
	v_mfma_f32_16x16x32_bf16 v[120:123], v[152:155], v[200:203], v[120:123]
	v_mfma_f32_16x16x32_bf16 v[108:111], v[134:137], v[208:211], v[108:111]
	v_mfma_f32_16x16x32_bf16 v[104:107], v[152:155], v[208:211], v[104:107]
	v_mfma_f32_16x16x32_bf16 v[92:95], v[134:137], v[216:219], v[92:95]
	v_mfma_f32_16x16x32_bf16 v[88:91], v[152:155], v[216:219], v[88:91]
	v_mfma_f32_16x16x32_bf16 v[76:79], v[134:137], v[224:227], v[76:79]
	v_mfma_f32_16x16x32_bf16 v[72:75], v[152:155], v[224:227], v[72:75]
	v_mfma_f32_16x16x32_bf16 v[116:119], v[156:159], v[196:199], v[116:119]
	v_mfma_f32_16x16x32_bf16 v[112:115], v[164:167], v[196:199], v[112:115]
	v_mfma_f32_16x16x32_bf16 v[100:103], v[156:159], v[204:207], v[100:103]
	v_mfma_f32_16x16x32_bf16 v[96:99], v[164:167], v[204:207], v[96:99]
	v_mfma_f32_16x16x32_bf16 v[84:87], v[156:159], v[212:215], v[84:87]
	v_mfma_f32_16x16x32_bf16 v[80:83], v[164:167], v[212:215], v[80:83]
	v_mfma_f32_16x16x32_bf16 v[68:71], v[156:159], v[220:223], v[68:71]
	v_mfma_f32_16x16x32_bf16 v[64:67], v[164:167], v[220:223], v[64:67]
	v_mfma_f32_16x16x32_bf16 v[116:119], v[160:163], v[200:203], v[116:119]
	v_mfma_f32_16x16x32_bf16 v[112:115], v[168:171], v[200:203], v[112:115]
	v_mfma_f32_16x16x32_bf16 v[100:103], v[160:163], v[208:211], v[100:103]
	v_mfma_f32_16x16x32_bf16 v[96:99], v[168:171], v[208:211], v[96:99]
	v_mfma_f32_16x16x32_bf16 v[84:87], v[160:163], v[216:219], v[84:87]
	v_mfma_f32_16x16x32_bf16 v[80:83], v[168:171], v[216:219], v[80:83]
	s_setprio 2
	s_barrier
	v_mfma_f32_16x16x32_bf16 v[68:71], v[160:163], v[224:227], v[68:71]
	v_mfma_f32_16x16x32_bf16 v[64:67], v[168:171], v[224:227], v[64:67]
	s_setprio 0
	s_add_i32 s14, s42, s49
	v_lshl_add_u64 v[228:229], v[228:229], 0, s[16:17]
	s_mov_b32 m0, s14
	ds_read_b128 v[196:199], v195 offset:49152
	ds_read_b128 v[200:203], v195 offset:50176
	ds_read_b128 v[204:207], v195 offset:51200
	ds_read_b128 v[208:211], v195 offset:52224
	ds_read_b128 v[212:215], v195 offset:53248
	ds_read_b128 v[216:219], v195 offset:54272
	ds_read_b128 v[220:223], v195 offset:55296
	ds_read_b128 v[224:227], v195 offset:56320
	global_load_lds_dwordx4 v[228:229], off
	v_lshl_add_u64 v[228:229], v[230:231], 0, s[16:17]
	s_add_i32 m0, s14, 0x2000
	s_add_i32 s14, s43, s49
	global_load_lds_dwordx4 v[228:229], off
	v_lshl_add_u64 v[228:229], v[232:233], 0, s[16:17]
	s_mov_b32 m0, s14
	s_nop 0
	global_load_lds_dwordx4 v[228:229], off
	v_lshl_add_u64 v[228:229], v[234:235], 0, s[16:17]
	s_add_i32 m0, s14, 0x2000
	s_nop 0
	global_load_lds_dwordx4 v[228:229], off
	v_lshl_add_u64 v[228:229], v[236:237], 0, s[16:17]
	s_mov_b32 m0, s72
	s_nop 0
	global_load_lds_dwordx4 v[228:229], off
	v_lshl_add_u64 v[228:229], v[238:239], 0, s[16:17]
	s_mov_b32 m0, s73
	s_nop 0
	global_load_lds_dwordx4 v[228:229], off
	s_waitcnt vmcnt(8)
	s_waitcnt lgkmcnt(0)
	s_barrier
	s_setprio 1
	s_waitcnt lgkmcnt(0)
	v_mfma_f32_16x16x32_bf16 v[60:63], v[130:133], v[196:199], v[60:63]
	v_mfma_f32_16x16x32_bf16 v[56:59], v[148:151], v[196:199], v[56:59]
	v_mfma_f32_16x16x32_bf16 v[44:47], v[130:133], v[204:207], v[44:47]
	v_mfma_f32_16x16x32_bf16 v[40:43], v[148:151], v[204:207], v[40:43]
	v_mfma_f32_16x16x32_bf16 v[28:31], v[130:133], v[212:215], v[28:31]
	v_mfma_f32_16x16x32_bf16 v[24:27], v[148:151], v[212:215], v[24:27]
	v_mfma_f32_16x16x32_bf16 v[12:15], v[130:133], v[220:223], v[12:15]
	v_mfma_f32_16x16x32_bf16 v[8:11], v[148:151], v[220:223], v[8:11]
	v_mfma_f32_16x16x32_bf16 v[60:63], v[134:137], v[200:203], v[60:63]
	v_mfma_f32_16x16x32_bf16 v[56:59], v[152:155], v[200:203], v[56:59]
	v_mfma_f32_16x16x32_bf16 v[44:47], v[134:137], v[208:211], v[44:47]
	v_mfma_f32_16x16x32_bf16 v[40:43], v[152:155], v[208:211], v[40:43]
	v_mfma_f32_16x16x32_bf16 v[28:31], v[134:137], v[216:219], v[28:31]
	v_mfma_f32_16x16x32_bf16 v[24:27], v[152:155], v[216:219], v[24:27]
	v_mfma_f32_16x16x32_bf16 v[12:15], v[134:137], v[224:227], v[12:15]
	v_mfma_f32_16x16x32_bf16 v[8:11], v[152:155], v[224:227], v[8:11]
	v_mfma_f32_16x16x32_bf16 v[52:55], v[156:159], v[196:199], v[52:55]
	v_mfma_f32_16x16x32_bf16 v[48:51], v[164:167], v[196:199], v[48:51]
	v_mfma_f32_16x16x32_bf16 v[36:39], v[156:159], v[204:207], v[36:39]
	v_mfma_f32_16x16x32_bf16 v[32:35], v[164:167], v[204:207], v[32:35]
	v_mfma_f32_16x16x32_bf16 v[20:23], v[156:159], v[212:215], v[20:23]
	v_mfma_f32_16x16x32_bf16 v[16:19], v[164:167], v[212:215], v[16:19]
	v_mfma_f32_16x16x32_bf16 v[4:7], v[156:159], v[220:223], v[4:7]
	v_mfma_f32_16x16x32_bf16 v[0:3], v[164:167], v[220:223], v[0:3]
	v_mfma_f32_16x16x32_bf16 v[52:55], v[160:163], v[200:203], v[52:55]
	v_mfma_f32_16x16x32_bf16 v[48:51], v[168:171], v[200:203], v[48:51]
	v_mfma_f32_16x16x32_bf16 v[36:39], v[160:163], v[208:211], v[36:39]
	v_mfma_f32_16x16x32_bf16 v[32:35], v[168:171], v[208:211], v[32:35]
	v_mfma_f32_16x16x32_bf16 v[20:23], v[160:163], v[216:219], v[20:23]
	v_mfma_f32_16x16x32_bf16 v[16:19], v[168:171], v[216:219], v[16:19]
	s_setprio 2
	s_barrier
	v_mfma_f32_16x16x32_bf16 v[4:7], v[160:163], v[224:227], v[4:7]
	v_mfma_f32_16x16x32_bf16 v[0:3], v[168:171], v[224:227], v[0:3]
	s_setprio 0
	s_add_i32 s89, s89, 2
	s_add_u32 s12, s12, 0x100
	s_addc_u32 s13, s13, 0
	s_add_u32 s87, s87, 0x100
	s_addc_u32 s88, s88, 0
	s_cmp_gt_u32 s89, 13
	s_cbranch_scc0 .LBB0_965
	s_and_b64 vcc, exec, s[26:27]
	s_cbranch_vccz .LBB0_968
	s_barrier

.LBB0_1511:
	v_add_u32_e32 v162, s50, v148
	v_add_u32_e32 v178, s51, v148
	s_add_u32 s34, s16, s26
	ds_read_b128 v[150:153], v162
	ds_read_b128 v[154:157], v162 offset:1024
	ds_read_b128 v[158:161], v162 offset:2048
	ds_read_b128 v[162:165], v162 offset:3072
	ds_read_b128 v[166:169], v178
	ds_read_b128 v[170:173], v178 offset:1024
	ds_read_b128 v[174:177], v178 offset:2048
	ds_read_b128 v[178:181], v178 offset:3072
	s_addc_u32 s35, s17, s27
	s_add_u32 s34, s34, 0x100
	s_addc_u32 s35, s35, 0
	s_add_u32 s57, s21, s26
	s_addc_u32 s58, s55, s27
	s_cmpk_eq_i32 s26, 0xf00
	s_cselect_b32 s37, s29, s35
	s_cselect_b32 s36, s28, s34
	s_cselect_b32 s35, s31, s58
	s_cselect_b32 s34, s30, s57
	v_lshl_add_u64 v[214:215], v[144:145], 0, s[26:27]
	s_add_i32 m0, s13, 0xc000
	ds_read_b128 v[182:185], v149
	ds_read_b128 v[186:189], v149 offset:1024
	ds_read_b128 v[190:193], v149 offset:2048
	ds_read_b128 v[194:197], v149 offset:3072
	ds_read_b128 v[198:201], v149 offset:4096
	ds_read_b128 v[202:205], v149 offset:5120
	ds_read_b128 v[206:209], v149 offset:6144
	ds_read_b128 v[210:213], v149 offset:7168
	global_load_lds_dwordx4 v[214:215], off
	v_lshl_add_u64 v[214:215], v[146:147], 0, s[26:27]
	s_add_i32 m0, s13, 0xe000
	s_nop 0
	global_load_lds_dwordx4 v[214:215], off
	s_waitcnt vmcnt(8)
	s_waitcnt lgkmcnt(0)
	s_barrier
	s_setprio 1
	s_waitcnt lgkmcnt(0)
	v_mfma_f32_16x16x32_bf16 v[128:131], v[150:153], v[182:185], v[128:131]
	v_mfma_f32_16x16x32_bf16 v[124:127], v[158:161], v[182:185], v[124:127]
	v_mfma_f32_16x16x32_bf16 v[116:119], v[150:153], v[190:193], v[116:119]
	v_mfma_f32_16x16x32_bf16 v[108:111], v[158:161], v[190:193], v[108:111]
	v_mfma_f32_16x16x32_bf16 v[100:103], v[150:153], v[198:201], v[100:103]
	v_mfma_f32_16x16x32_bf16 v[92:95], v[158:161], v[198:201], v[92:95]
	v_mfma_f32_16x16x32_bf16 v[84:87], v[150:153], v[206:209], v[84:87]
	v_mfma_f32_16x16x32_bf16 v[76:79], v[158:161], v[206:209], v[76:79]
	v_mfma_f32_16x16x32_bf16 v[128:131], v[154:157], v[186:189], v[128:131]
	v_mfma_f32_16x16x32_bf16 v[124:127], v[162:165], v[186:189], v[124:127]
	v_mfma_f32_16x16x32_bf16 v[116:119], v[154:157], v[194:197], v[116:119]
	v_mfma_f32_16x16x32_bf16 v[108:111], v[162:165], v[194:197], v[108:111]
	v_mfma_f32_16x16x32_bf16 v[100:103], v[154:157], v[202:205], v[100:103]
	v_mfma_f32_16x16x32_bf16 v[92:95], v[162:165], v[202:205], v[92:95]
	v_mfma_f32_16x16x32_bf16 v[84:87], v[154:157], v[210:213], v[84:87]
	v_mfma_f32_16x16x32_bf16 v[76:79], v[162:165], v[210:213], v[76:79]
	v_mfma_f32_16x16x32_bf16 v[120:123], v[166:169], v[182:185], v[120:123]
	v_mfma_f32_16x16x32_bf16 v[112:115], v[174:177], v[182:185], v[112:115]
	v_mfma_f32_16x16x32_bf16 v[104:107], v[166:169], v[190:193], v[104:107]
	v_mfma_f32_16x16x32_bf16 v[96:99], v[174:177], v[190:193], v[96:99]
	v_mfma_f32_16x16x32_bf16 v[88:91], v[166:169], v[198:201], v[88:91]
	v_mfma_f32_16x16x32_bf16 v[80:83], v[174:177], v[198:201], v[80:83]
	v_mfma_f32_16x16x32_bf16 v[72:75], v[166:169], v[206:209], v[72:75]
	v_mfma_f32_16x16x32_bf16 v[68:71], v[174:177], v[206:209], v[68:71]
	v_mfma_f32_16x16x32_bf16 v[120:123], v[170:173], v[186:189], v[120:123]
	v_mfma_f32_16x16x32_bf16 v[112:115], v[178:181], v[186:189], v[112:115]
	v_mfma_f32_16x16x32_bf16 v[104:107], v[170:173], v[194:197], v[104:107]
	v_mfma_f32_16x16x32_bf16 v[96:99], v[178:181], v[194:197], v[96:99]
	v_mfma_f32_16x16x32_bf16 v[88:91], v[170:173], v[202:205], v[88:91]
	v_mfma_f32_16x16x32_bf16 v[80:83], v[178:181], v[202:205], v[80:83]
	s_setprio 2
	s_barrier
	v_mfma_f32_16x16x32_bf16 v[72:75], v[170:173], v[210:213], v[72:75]
	v_mfma_f32_16x16x32_bf16 v[68:71], v[178:181], v[210:213], v[68:71]
	s_setprio 0
	s_add_i32 s57, s50, s42
	v_lshl_add_u64 v[214:215], s[34:35], 0, v[2:3]
	s_mov_b32 m0, s57
	ds_read_b128 v[182:185], v149 offset:16384
	ds_read_b128 v[186:189], v149 offset:17408
	ds_read_b128 v[190:193], v149 offset:18432
	ds_read_b128 v[194:197], v149 offset:19456
	ds_read_b128 v[198:201], v149 offset:20480
	ds_read_b128 v[202:205], v149 offset:21504
	ds_read_b128 v[206:209], v149 offset:22528
	ds_read_b128 v[210:213], v149 offset:23552
	global_load_lds_dwordx4 v[214:215], off
	s_add_i32 m0, s57, 0x2000
	s_add_u32 s58, s34, 0x80000
	v_lshl_add_u64 v[216:217], s[34:35], 0, v[134:135]
	s_addc_u32 s59, s35, 0
	s_add_i32 s57, s51, s42
	global_load_lds_dwordx4 v[216:217], off
	v_lshl_add_u64 v[218:219], s[58:59], 0, v[2:3]
	s_mov_b32 m0, s57
	v_lshl_add_u64 v[220:221], s[36:37], 0, v[132:133]
	global_load_lds_dwordx4 v[218:219], off
	v_lshl_add_u64 v[218:219], s[58:59], 0, v[134:135]
	s_add_i32 m0, s57, 0x2000
	s_nop 0
	global_load_lds_dwordx4 v[218:219], off
	v_lshl_add_u64 v[218:219], s[36:37], 0, v[0:1]
	s_mov_b32 m0, s13
	s_nop 0
	global_load_lds_dwordx4 v[218:219], off
	s_mov_b32 m0, s43
	s_nop 0
	global_load_lds_dwordx4 v[220:221], off
	s_waitcnt vmcnt(8)
	s_waitcnt lgkmcnt(0)
	s_barrier
	s_setprio 1
	s_waitcnt lgkmcnt(0)
	v_mfma_f32_16x16x32_bf16 v[64:67], v[150:153], v[182:185], v[64:67]
	v_mfma_f32_16x16x32_bf16 v[60:63], v[158:161], v[182:185], v[60:63]
	v_mfma_f32_16x16x32_bf16 v[52:55], v[150:153], v[190:193], v[52:55]
	v_mfma_f32_16x16x32_bf16 v[44:47], v[158:161], v[190:193], v[44:47]
	v_mfma_f32_16x16x32_bf16 v[36:39], v[150:153], v[198:201], v[36:39]
	v_mfma_f32_16x16x32_bf16 v[28:31], v[158:161], v[198:201], v[28:31]
	v_mfma_f32_16x16x32_bf16 v[20:23], v[150:153], v[206:209], v[20:23]
	v_mfma_f32_16x16x32_bf16 v[12:15], v[158:161], v[206:209], v[12:15]
	v_mfma_f32_16x16x32_bf16 v[64:67], v[154:157], v[186:189], v[64:67]
	v_mfma_f32_16x16x32_bf16 v[60:63], v[162:165], v[186:189], v[60:63]
	v_mfma_f32_16x16x32_bf16 v[52:55], v[154:157], v[194:197], v[52:55]
	v_mfma_f32_16x16x32_bf16 v[44:47], v[162:165], v[194:197], v[44:47]
	v_mfma_f32_16x16x32_bf16 v[36:39], v[154:157], v[202:205], v[36:39]
	v_mfma_f32_16x16x32_bf16 v[28:31], v[162:165], v[202:205], v[28:31]
	v_mfma_f32_16x16x32_bf16 v[20:23], v[154:157], v[210:213], v[20:23]
	v_mfma_f32_16x16x32_bf16 v[12:15], v[162:165], v[210:213], v[12:15]
	v_mfma_f32_16x16x32_bf16 v[56:59], v[166:169], v[182:185], v[56:59]
	v_mfma_f32_16x16x32_bf16 v[48:51], v[174:177], v[182:185], v[48:51]
	v_mfma_f32_16x16x32_bf16 v[40:43], v[166:169], v[190:193], v[40:43]
	v_mfma_f32_16x16x32_bf16 v[32:35], v[174:177], v[190:193], v[32:35]
	v_mfma_f32_16x16x32_bf16 v[24:27], v[166:169], v[198:201], v[24:27]
	v_mfma_f32_16x16x32_bf16 v[16:19], v[174:177], v[198:201], v[16:19]
	v_mfma_f32_16x16x32_bf16 v[8:11], v[166:169], v[206:209], v[8:11]
	v_mfma_f32_16x16x32_bf16 v[4:7], v[174:177], v[206:209], v[4:7]
	v_mfma_f32_16x16x32_bf16 v[56:59], v[170:173], v[186:189], v[56:59]
	v_mfma_f32_16x16x32_bf16 v[48:51], v[178:181], v[186:189], v[48:51]
	v_mfma_f32_16x16x32_bf16 v[40:43], v[170:173], v[194:197], v[40:43]
	v_mfma_f32_16x16x32_bf16 v[32:35], v[178:181], v[194:197], v[32:35]
	v_mfma_f32_16x16x32_bf16 v[24:27], v[170:173], v[202:205], v[24:27]
	v_mfma_f32_16x16x32_bf16 v[16:19], v[178:181], v[202:205], v[16:19]
	s_setprio 2
	s_barrier
	v_mfma_f32_16x16x32_bf16 v[8:11], v[170:173], v[210:213], v[8:11]
	v_mfma_f32_16x16x32_bf16 v[4:7], v[178:181], v[210:213], v[4:7]
	s_setprio 0
	s_add_i32 s57, 0, 0x18000
	s_add_i32 s58, 0, 0x1c000
	v_add_u32_e32 v162, s57, v148
	v_add_u32_e32 v178, s58, v148
	ds_read_b128 v[150:153], v162
	ds_read_b128 v[154:157], v162 offset:1024
	ds_read_b128 v[158:161], v162 offset:2048
	ds_read_b128 v[162:165], v162 offset:3072
	ds_read_b128 v[166:169], v178
	ds_read_b128 v[170:173], v178 offset:1024
	ds_read_b128 v[174:177], v178 offset:2048
	ds_read_b128 v[178:181], v178 offset:3072
	s_add_u32 s36, s36, 0x80000
	s_addc_u32 s37, s37, 0
	s_mov_b32 m0, s45
	v_lshl_add_u64 v[222:223], s[36:37], 0, v[0:1]
	ds_read_b128 v[182:185], v149 offset:32768
	ds_read_b128 v[186:189], v149 offset:33792
	ds_read_b128 v[190:193], v149 offset:34816
	ds_read_b128 v[194:197], v149 offset:35840
	ds_read_b128 v[198:201], v149 offset:36864
	ds_read_b128 v[202:205], v149 offset:37888
	ds_read_b128 v[206:209], v149 offset:38912
	ds_read_b128 v[210:213], v149 offset:39936
	global_load_lds_dwordx4 v[222:223], off
	v_lshl_add_u64 v[222:223], s[36:37], 0, v[132:133]
	s_mov_b32 m0, s46
	s_nop 0
	global_load_lds_dwordx4 v[222:223], off
	s_waitcnt vmcnt(8)
	s_waitcnt lgkmcnt(0)
	s_barrier
	s_setprio 1
	s_waitcnt lgkmcnt(0)
	v_mfma_f32_16x16x32_bf16 v[128:131], v[150:153], v[182:185], v[128:131]
	v_mfma_f32_16x16x32_bf16 v[124:127], v[158:161], v[182:185], v[124:127]
	v_mfma_f32_16x16x32_bf16 v[116:119], v[150:153], v[190:193], v[116:119]
	v_mfma_f32_16x16x32_bf16 v[108:111], v[158:161], v[190:193], v[108:111]
	v_mfma_f32_16x16x32_bf16 v[100:103], v[150:153], v[198:201], v[100:103]
	v_mfma_f32_16x16x32_bf16 v[92:95], v[158:161], v[198:201], v[92:95]
	v_mfma_f32_16x16x32_bf16 v[84:87], v[150:153], v[206:209], v[84:87]
	v_mfma_f32_16x16x32_bf16 v[76:79], v[158:161], v[206:209], v[76:79]
	v_mfma_f32_16x16x32_bf16 v[128:131], v[154:157], v[186:189], v[128:131]
	v_mfma_f32_16x16x32_bf16 v[124:127], v[162:165], v[186:189], v[124:127]
	v_mfma_f32_16x16x32_bf16 v[116:119], v[154:157], v[194:197], v[116:119]
	v_mfma_f32_16x16x32_bf16 v[108:111], v[162:165], v[194:197], v[108:111]
	v_mfma_f32_16x16x32_bf16 v[100:103], v[154:157], v[202:205], v[100:103]
	v_mfma_f32_16x16x32_bf16 v[92:95], v[162:165], v[202:205], v[92:95]
	v_mfma_f32_16x16x32_bf16 v[84:87], v[154:157], v[210:213], v[84:87]
	v_mfma_f32_16x16x32_bf16 v[76:79], v[162:165], v[210:213], v[76:79]
	v_mfma_f32_16x16x32_bf16 v[120:123], v[166:169], v[182:185], v[120:123]
	v_mfma_f32_16x16x32_bf16 v[112:115], v[174:177], v[182:185], v[112:115]
	v_mfma_f32_16x16x32_bf16 v[104:107], v[166:169], v[190:193], v[104:107]
	v_mfma_f32_16x16x32_bf16 v[96:99], v[174:177], v[190:193], v[96:99]
	v_mfma_f32_16x16x32_bf16 v[88:91], v[166:169], v[198:201], v[88:91]
	v_mfma_f32_16x16x32_bf16 v[80:83], v[174:177], v[198:201], v[80:83]
	v_mfma_f32_16x16x32_bf16 v[72:75], v[166:169], v[206:209], v[72:75]
	v_mfma_f32_16x16x32_bf16 v[68:71], v[174:177], v[206:209], v[68:71]
	v_mfma_f32_16x16x32_bf16 v[120:123], v[170:173], v[186:189], v[120:123]
	v_mfma_f32_16x16x32_bf16 v[112:115], v[178:181], v[186:189], v[112:115]
	v_mfma_f32_16x16x32_bf16 v[104:107], v[170:173], v[194:197], v[104:107]
	v_mfma_f32_16x16x32_bf16 v[96:99], v[178:181], v[194:197], v[96:99]
	v_mfma_f32_16x16x32_bf16 v[88:91], v[170:173], v[202:205], v[88:91]
	v_mfma_f32_16x16x32_bf16 v[80:83], v[178:181], v[202:205], v[80:83]
	s_setprio 2
	s_barrier
	v_mfma_f32_16x16x32_bf16 v[72:75], v[170:173], v[210:213], v[72:75]
	v_mfma_f32_16x16x32_bf16 v[68:71], v[178:181], v[210:213], v[68:71]
	s_setprio 0
	s_add_i32 s36, s57, s42
	v_lshl_add_u64 v[214:215], v[214:215], 0, s[18:19]
	s_mov_b32 m0, s36
	ds_read_b128 v[182:185], v149 offset:49152
	ds_read_b128 v[186:189], v149 offset:50176
	ds_read_b128 v[190:193], v149 offset:51200
	ds_read_b128 v[194:197], v149 offset:52224
	ds_read_b128 v[198:201], v149 offset:53248
	ds_read_b128 v[202:205], v149 offset:54272
	ds_read_b128 v[206:209], v149 offset:55296
	ds_read_b128 v[210:213], v149 offset:56320
	global_load_lds_dwordx4 v[214:215], off
	s_add_i32 m0, s36, 0x2000
	s_add_u32 s34, s34, 0x80080
	v_lshl_add_u64 v[214:215], v[216:217], 0, s[18:19]
	s_addc_u32 s35, s35, 0
	s_add_i32 s36, s58, s42
	global_load_lds_dwordx4 v[214:215], off
	v_lshl_add_u64 v[214:215], s[34:35], 0, v[2:3]
	s_mov_b32 m0, s36
	s_nop 0
	global_load_lds_dwordx4 v[214:215], off
	v_lshl_add_u64 v[214:215], s[34:35], 0, v[134:135]
	s_add_i32 m0, s36, 0x2000
	s_nop 0
	global_load_lds_dwordx4 v[214:215], off
	v_lshl_add_u64 v[214:215], v[218:219], 0, s[18:19]
	s_mov_b32 m0, s48
	s_nop 0
	global_load_lds_dwordx4 v[214:215], off
	v_lshl_add_u64 v[214:215], v[220:221], 0, s[18:19]
	s_mov_b32 m0, s49
	s_nop 0
	global_load_lds_dwordx4 v[214:215], off
	s_waitcnt vmcnt(8)
	s_waitcnt lgkmcnt(0)
	s_barrier
	s_setprio 1
	s_waitcnt lgkmcnt(0)
	v_mfma_f32_16x16x32_bf16 v[64:67], v[150:153], v[182:185], v[64:67]
	v_mfma_f32_16x16x32_bf16 v[60:63], v[158:161], v[182:185], v[60:63]
	v_mfma_f32_16x16x32_bf16 v[52:55], v[150:153], v[190:193], v[52:55]
	v_mfma_f32_16x16x32_bf16 v[44:47], v[158:161], v[190:193], v[44:47]
	v_mfma_f32_16x16x32_bf16 v[36:39], v[150:153], v[198:201], v[36:39]
	v_mfma_f32_16x16x32_bf16 v[28:31], v[158:161], v[198:201], v[28:31]
	v_mfma_f32_16x16x32_bf16 v[20:23], v[150:153], v[206:209], v[20:23]
	v_mfma_f32_16x16x32_bf16 v[12:15], v[158:161], v[206:209], v[12:15]
	v_mfma_f32_16x16x32_bf16 v[64:67], v[154:157], v[186:189], v[64:67]
	v_mfma_f32_16x16x32_bf16 v[60:63], v[162:165], v[186:189], v[60:63]
	v_mfma_f32_16x16x32_bf16 v[52:55], v[154:157], v[194:197], v[52:55]
	v_mfma_f32_16x16x32_bf16 v[44:47], v[162:165], v[194:197], v[44:47]
	v_mfma_f32_16x16x32_bf16 v[36:39], v[154:157], v[202:205], v[36:39]
	v_mfma_f32_16x16x32_bf16 v[28:31], v[162:165], v[202:205], v[28:31]
	v_mfma_f32_16x16x32_bf16 v[20:23], v[154:157], v[210:213], v[20:23]
	v_mfma_f32_16x16x32_bf16 v[12:15], v[162:165], v[210:213], v[12:15]
	v_mfma_f32_16x16x32_bf16 v[56:59], v[166:169], v[182:185], v[56:59]
	v_mfma_f32_16x16x32_bf16 v[48:51], v[174:177], v[182:185], v[48:51]
	v_mfma_f32_16x16x32_bf16 v[40:43], v[166:169], v[190:193], v[40:43]
	v_mfma_f32_16x16x32_bf16 v[32:35], v[174:177], v[190:193], v[32:35]
	v_mfma_f32_16x16x32_bf16 v[24:27], v[166:169], v[198:201], v[24:27]
	v_mfma_f32_16x16x32_bf16 v[16:19], v[174:177], v[198:201], v[16:19]
	v_mfma_f32_16x16x32_bf16 v[8:11], v[166:169], v[206:209], v[8:11]
	v_mfma_f32_16x16x32_bf16 v[4:7], v[174:177], v[206:209], v[4:7]
	v_mfma_f32_16x16x32_bf16 v[56:59], v[170:173], v[186:189], v[56:59]
	v_mfma_f32_16x16x32_bf16 v[48:51], v[178:181], v[186:189], v[48:51]
	v_mfma_f32_16x16x32_bf16 v[40:43], v[170:173], v[194:197], v[40:43]
	v_mfma_f32_16x16x32_bf16 v[32:35], v[178:181], v[194:197], v[32:35]
	v_mfma_f32_16x16x32_bf16 v[24:27], v[170:173], v[202:205], v[24:27]
	v_mfma_f32_16x16x32_bf16 v[16:19], v[178:181], v[202:205], v[16:19]
	s_setprio 2
	s_barrier
	v_mfma_f32_16x16x32_bf16 v[8:11], v[170:173], v[210:213], v[8:11]
	v_mfma_f32_16x16x32_bf16 v[4:7], v[178:181], v[210:213], v[4:7]
	s_setprio 0
	s_add_i32 s56, s56, 2
	s_add_u32 s26, s26, 0x100
	s_addc_u32 s27, s27, 0
	s_cmp_gt_u32 s56, 29
	s_cbranch_scc0 .LBB0_1511
	s_add_u32 s26, s21, 0xffffff00
	s_addc_u32 s27, s55, -1
	s_andn2_b64 vcc, exec, s[4:5]
	s_cbranch_vccnz .LBB0_1503
	v_mov_b32_e32 v4, 0
	s_mov_b32 s14, s53
	s_mov_b32 s12, s20
	s_mov_b64 s[26:27], s[24:25]
	s_mov_b64 s[16:17], s[22:23]
	s_mov_b32 s47, s54
	v_mov_b32_e32 v5, v4
	v_mov_b32_e32 v6, v4
	v_mov_b32_e32 v7, v4
	v_mov_b32_e32 v8, v4
	v_mov_b32_e32 v9, v4
	v_mov_b32_e32 v10, v4
	v_mov_b32_e32 v11, v4
	v_mov_b32_e32 v16, v4
	v_mov_b32_e32 v17, v4
	v_mov_b32_e32 v18, v4
	v_mov_b32_e32 v19, v4
	v_mov_b32_e32 v24, v4
	v_mov_b32_e32 v25, v4
	v_mov_b32_e32 v26, v4
	v_mov_b32_e32 v27, v4
	v_mov_b32_e32 v32, v4
	v_mov_b32_e32 v33, v4
	v_mov_b32_e32 v34, v4
	v_mov_b32_e32 v35, v4
	v_mov_b32_e32 v40, v4
	v_mov_b32_e32 v41, v4
	v_mov_b32_e32 v42, v4
	v_mov_b32_e32 v43, v4
	v_mov_b32_e32 v48, v4
	v_mov_b32_e32 v49, v4
	v_mov_b32_e32 v50, v4
	v_mov_b32_e32 v51, v4
	v_mov_b32_e32 v56, v4
	v_mov_b32_e32 v57, v4
	v_mov_b32_e32 v58, v4
	v_mov_b32_e32 v59, v4
	v_mov_b32_e32 v12, v4
	v_mov_b32_e32 v13, v4
	v_mov_b32_e32 v14, v4
	v_mov_b32_e32 v15, v4
	v_mov_b32_e32 v20, v4
	v_mov_b32_e32 v21, v4
	v_mov_b32_e32 v22, v4
	v_mov_b32_e32 v23, v4
	v_mov_b32_e32 v28, v4
	v_mov_b32_e32 v29, v4
	v_mov_b32_e32 v30, v4
	v_mov_b32_e32 v31, v4
	v_mov_b32_e32 v36, v4
	v_mov_b32_e32 v37, v4
	v_mov_b32_e32 v38, v4
	v_mov_b32_e32 v39, v4
	v_mov_b32_e32 v44, v4
	v_mov_b32_e32 v45, v4
	v_mov_b32_e32 v46, v4
	v_mov_b32_e32 v47, v4
	v_mov_b32_e32 v52, v4
	v_mov_b32_e32 v53, v4
	v_mov_b32_e32 v54, v4
	v_mov_b32_e32 v55, v4
	v_mov_b32_e32 v60, v4
	v_mov_b32_e32 v61, v4
	v_mov_b32_e32 v62, v4
	v_mov_b32_e32 v63, v4
	v_mov_b32_e32 v64, v4
	v_mov_b32_e32 v65, v4
	v_mov_b32_e32 v66, v4
	v_mov_b32_e32 v67, v4
	v_mov_b32_e32 v68, v4
	v_mov_b32_e32 v69, v4
	v_mov_b32_e32 v70, v4
	v_mov_b32_e32 v71, v4
	v_mov_b32_e32 v72, v4
	v_mov_b32_e32 v73, v4
	v_mov_b32_e32 v74, v4
	v_mov_b32_e32 v75, v4
	v_mov_b32_e32 v80, v4
	v_mov_b32_e32 v81, v4
	v_mov_b32_e32 v82, v4
	v_mov_b32_e32 v83, v4
	v_mov_b32_e32 v88, v4
	v_mov_b32_e32 v89, v4
	v_mov_b32_e32 v90, v4
	v_mov_b32_e32 v91, v4
	v_mov_b32_e32 v96, v4
	v_mov_b32_e32 v97, v4
	v_mov_b32_e32 v98, v4
	v_mov_b32_e32 v99, v4
	v_mov_b32_e32 v104, v4
	v_mov_b32_e32 v105, v4
	v_mov_b32_e32 v106, v4
	v_mov_b32_e32 v107, v4
	v_mov_b32_e32 v112, v4
	v_mov_b32_e32 v113, v4
	v_mov_b32_e32 v114, v4
	v_mov_b32_e32 v115, v4
	v_mov_b32_e32 v120, v4
	v_mov_b32_e32 v121, v4
	v_mov_b32_e32 v122, v4
	v_mov_b32_e32 v123, v4
	v_mov_b32_e32 v76, v4
	v_mov_b32_e32 v77, v4
	v_mov_b32_e32 v78, v4
	v_mov_b32_e32 v79, v4
	v_mov_b32_e32 v84, v4
	v_mov_b32_e32 v85, v4
	v_mov_b32_e32 v86, v4
	v_mov_b32_e32 v87, v4
	v_mov_b32_e32 v92, v4
	v_mov_b32_e32 v93, v4
	v_mov_b32_e32 v94, v4
	v_mov_b32_e32 v95, v4
	v_mov_b32_e32 v100, v4
	v_mov_b32_e32 v101, v4
	v_mov_b32_e32 v102, v4
	v_mov_b32_e32 v103, v4
	v_mov_b32_e32 v108, v4
	v_mov_b32_e32 v109, v4
	v_mov_b32_e32 v110, v4
	v_mov_b32_e32 v111, v4
	v_mov_b32_e32 v116, v4
	v_mov_b32_e32 v117, v4
	v_mov_b32_e32 v118, v4
	v_mov_b32_e32 v119, v4
	v_mov_b32_e32 v124, v4
	v_mov_b32_e32 v125, v4
	v_mov_b32_e32 v126, v4
	v_mov_b32_e32 v127, v4
	v_mov_b32_e32 v128, v4
	v_mov_b32_e32 v129, v4
	v_mov_b32_e32 v130, v4
	v_mov_b32_e32 v131, v4
	s_branch .LBB0_1503
